# P3 k-norm row loop: four rows per trip, loads issued together, lane reductions interleaved
# speedup vs baseline: 1.0088x; 1.0088x over previous
.LBB0_137:
	s_lshl_b32 s0, s0, 3
	s_add_i32 s0, s76, s0
	s_lshl_b32 s1, s85, 3
	s_cmpk_gt_i32 s0, 0x7fff
	s_waitcnt vmcnt(0)
	s_barrier
	s_cbranch_scc1 .LBB0_140
	v_lshlrev_b32_e32 v6, 2, v136
	v_mov_b32_e32 v0, 0x400
	v_mov_b32_e32 v1, 0x300
	v_cmp_gt_u32_e32 vcc, 32, v137
	v_bfe_u32 v8, v136, 4, 1
	v_and_b32_e32 v7, 60, v6
	v_cndmask_b32_e32 v0, v0, v1, vcc
	v_lshlrev_b32_e32 v1, 6, v8
	v_or3_b32 v0, v0, v1, v7
	v_lshlrev_b32_e32 v0, 1, v0
	v_mov_b32_e32 v1, 0
	v_lshl_add_u64 v[2:3], s[34:35], 0, v[0:1]
	v_mbcnt_lo_u32_b32 v0, -1, 0
	v_mbcnt_hi_u32_b32 v0, -1, v0
	v_and_b32_e32 v5, 64, v0
	v_xor_b32_e32 v4, 1, v0
	v_add_u32_e32 v5, 64, v5
	v_cmp_lt_i32_e64 s[8:9], v4, v5
	v_and_b32_e32 v16, 4, v6
	v_mov_b32_e32 v6, 0x142e0800
	v_cndmask_b32_e64 v4, v0, v4, s[8:9]
	v_lshlrev_b32_e32 v9, 2, v4
	v_xor_b32_e32 v4, 2, v0
	v_cmp_lt_i32_e64 s[8:9], v4, v5
	v_mov_b32_e32 v14, 0x1800
	v_mov_b32_e32 v15, 0x358637bd
	v_cndmask_b32_e64 v4, v0, v4, s[8:9]
	v_lshlrev_b32_e32 v10, 2, v4
	v_xor_b32_e32 v4, 4, v0
	v_cmp_lt_i32_e64 s[8:9], v4, v5
	s_nop 1
	v_cndmask_b32_e64 v4, v0, v4, s[8:9]
	v_lshlrev_b32_e32 v11, 2, v4
	v_xor_b32_e32 v4, 8, v0
	v_cmp_lt_i32_e64 s[8:9], v4, v5
	s_nop 1
	v_cndmask_b32_e64 v0, v0, v4, s[8:9]
	v_lshlrev_b32_e32 v12, 2, v0
	v_mov_b32_e32 v0, s49
	v_mov_b32_e32 v4, s47
	v_cndmask_b32_e32 v5, v0, v4, vcc
	v_mov_b32_e32 v0, s48
	v_mov_b32_e32 v4, s46
	v_cndmask_b32_e32 v4, v0, v4, vcc
	v_lshlrev_b32_e32 v0, 2, v7
	v_lshl_add_u64 v[4:5], v[4:5], 0, v[0:1]
	v_mov_b32_e32 v0, 0x14ae0800
	v_cndmask_b32_e32 v0, v0, v6, vcc
	v_lshl_add_u64 v[6:7], s[68:69], 0, v[0:1]
	v_lshlrev_b32_e32 v0, 3, v136
	v_and_b32_e32 v13, 0x70, v0
	s_mov_b32 s8, 0x800000
	v_lshlrev_b32_e32 v0, 1, v16
	s_mov_b32 s9, s0
	global_load_dwordx4 v[32:35], v[4:5], off
.Lkn4_loop:
	s_mul_i32 s20, s1, 3
	s_add_i32 s20, s20, s9
	s_cmpk_gt_i32 s20, 0x7fff
	s_cbranch_scc1 .Lkn4_rest
	s_mov_b32 s16, s9
	s_add_i32 s17, s16, s1
	s_add_i32 s18, s17, s1
	s_add_i32 s19, s18, s1
	v_mad_i64_i32 v[40:41], s[4:5], s16, v14, v[2:3]
	v_mad_i64_i32 v[42:43], s[4:5], s17, v14, v[2:3]
	v_mad_i64_i32 v[44:45], s[4:5], s18, v14, v[2:3]
	v_mad_i64_i32 v[46:47], s[4:5], s19, v14, v[2:3]
	global_load_dwordx2 v[56:57], v[40:41], off
	global_load_dwordx2 v[58:59], v[42:43], off
	global_load_dwordx2 v[60:61], v[44:45], off
	global_load_dwordx2 v[62:63], v[46:47], off
	s_ashr_i32 s4, s16, 31
	s_lshr_b32 s4, s4, 20
	s_add_i32 s4, s16, s4
	s_ashr_i32 s5, s4, 12
	s_and_b32 s4, s4, 0xfffff000
	s_sub_i32 s4, s16, s4
	v_lshl_or_b32 v64, s5, 1, v8
	s_bfe_u32 s5, s4, 0x10002
	s_lshr_b32 s10, s4, 1
	s_and_b32 s11, s4, 3
	s_lshr_b32 s4, s4, 4
	s_and_b32 s4, s4, 0x1fffffe
	s_and_b32 s10, s10, 12
	s_or_b32 s4, s4, s5
	v_ashrrev_i32_e32 v65, 31, v64
	s_or_b32 s10, s11, s10
	v_lshl_or_b32 v36, s4, 7, v13
	v_lshlrev_b64 v[64:65], 19, v[64:65]
	v_or_b32_e32 v36, s10, v36
	v_lshl_add_u64 v[64:65], v[6:7], 0, v[64:65]
	v_ashrrev_i32_e32 v37, 31, v36
	v_lshl_add_u64 v[64:65], v[36:37], 4, v[64:65]
	v_lshl_add_u64 v[64:65], v[64:65], 0, v[0:1]
	s_ashr_i32 s4, s17, 31
	s_lshr_b32 s4, s4, 20
	s_add_i32 s4, s17, s4
	s_ashr_i32 s5, s4, 12
	s_and_b32 s4, s4, 0xfffff000
	s_sub_i32 s4, s17, s4
	v_lshl_or_b32 v66, s5, 1, v8
	s_bfe_u32 s5, s4, 0x10002
	s_lshr_b32 s10, s4, 1
	s_and_b32 s11, s4, 3
	s_lshr_b32 s4, s4, 4
	s_and_b32 s4, s4, 0x1fffffe
	s_and_b32 s10, s10, 12
	s_or_b32 s4, s4, s5
	v_ashrrev_i32_e32 v67, 31, v66
	s_or_b32 s10, s11, s10
	v_lshl_or_b32 v36, s4, 7, v13
	v_lshlrev_b64 v[66:67], 19, v[66:67]
	v_or_b32_e32 v36, s10, v36
	v_lshl_add_u64 v[66:67], v[6:7], 0, v[66:67]
	v_ashrrev_i32_e32 v37, 31, v36
	v_lshl_add_u64 v[66:67], v[36:37], 4, v[66:67]
	v_lshl_add_u64 v[66:67], v[66:67], 0, v[0:1]
	s_ashr_i32 s4, s18, 31
	s_lshr_b32 s4, s4, 20
	s_add_i32 s4, s18, s4
	s_ashr_i32 s5, s4, 12
	s_and_b32 s4, s4, 0xfffff000
	s_sub_i32 s4, s18, s4
	v_lshl_or_b32 v68, s5, 1, v8
	s_bfe_u32 s5, s4, 0x10002
	s_lshr_b32 s10, s4, 1
	s_and_b32 s11, s4, 3
	s_lshr_b32 s4, s4, 4
	s_and_b32 s4, s4, 0x1fffffe
	s_and_b32 s10, s10, 12
	s_or_b32 s4, s4, s5
	v_ashrrev_i32_e32 v69, 31, v68
	s_or_b32 s10, s11, s10
	v_lshl_or_b32 v36, s4, 7, v13
	v_lshlrev_b64 v[68:69], 19, v[68:69]
	v_or_b32_e32 v36, s10, v36
	v_lshl_add_u64 v[68:69], v[6:7], 0, v[68:69]
	v_ashrrev_i32_e32 v37, 31, v36
	v_lshl_add_u64 v[68:69], v[36:37], 4, v[68:69]
	v_lshl_add_u64 v[68:69], v[68:69], 0, v[0:1]
	s_ashr_i32 s4, s19, 31
	s_lshr_b32 s4, s4, 20
	s_add_i32 s4, s19, s4
	s_ashr_i32 s5, s4, 12
	s_and_b32 s4, s4, 0xfffff000
	s_sub_i32 s4, s19, s4
	v_lshl_or_b32 v70, s5, 1, v8
	s_bfe_u32 s5, s4, 0x10002
	s_lshr_b32 s10, s4, 1
	s_and_b32 s11, s4, 3
	s_lshr_b32 s4, s4, 4
	s_and_b32 s4, s4, 0x1fffffe
	s_and_b32 s10, s10, 12
	s_or_b32 s4, s4, s5
	v_ashrrev_i32_e32 v71, 31, v70
	s_or_b32 s10, s11, s10
	v_lshl_or_b32 v36, s4, 7, v13
	v_lshlrev_b64 v[70:71], 19, v[70:71]
	v_or_b32_e32 v36, s10, v36
	v_lshl_add_u64 v[70:71], v[6:7], 0, v[70:71]
	v_ashrrev_i32_e32 v37, 31, v36
	v_lshl_add_u64 v[70:71], v[36:37], 4, v[70:71]
	v_lshl_add_u64 v[70:71], v[70:71], 0, v[0:1]
	s_add_i32 s9, s19, s1
	s_waitcnt vmcnt(0)
	v_lshlrev_b32_e32 v72, 16, v56
	v_and_b32_e32 v73, 0xffff0000, v56
	v_lshlrev_b32_e32 v74, 16, v57
	v_and_b32_e32 v75, 0xffff0000, v57
	v_lshlrev_b32_e32 v76, 16, v58
	v_and_b32_e32 v77, 0xffff0000, v58
	v_lshlrev_b32_e32 v78, 16, v59
	v_and_b32_e32 v79, 0xffff0000, v59
	v_lshlrev_b32_e32 v80, 16, v60
	v_and_b32_e32 v81, 0xffff0000, v60
	v_lshlrev_b32_e32 v82, 16, v61
	v_and_b32_e32 v83, 0xffff0000, v61
	v_lshlrev_b32_e32 v84, 16, v62
	v_and_b32_e32 v85, 0xffff0000, v62
	v_lshlrev_b32_e32 v86, 16, v63
	v_and_b32_e32 v87, 0xffff0000, v63
	v_mul_f32_e32 v88, v73, v73
	v_mul_f32_e32 v92, v75, v75
	v_mul_f32_e32 v89, v77, v77
	v_mul_f32_e32 v93, v79, v79
	v_mul_f32_e32 v90, v81, v81
	v_mul_f32_e32 v94, v83, v83
	v_mul_f32_e32 v91, v85, v85
	v_mul_f32_e32 v95, v87, v87
	v_fmac_f32_e32 v88, v72, v72
	v_fmac_f32_e32 v92, v74, v74
	v_fmac_f32_e32 v89, v76, v76
	v_fmac_f32_e32 v93, v78, v78
	v_fmac_f32_e32 v90, v80, v80
	v_fmac_f32_e32 v94, v82, v82
	v_fmac_f32_e32 v91, v84, v84
	v_fmac_f32_e32 v95, v86, v86
	v_add_f32_e32 v88, v88, v92
	v_add_f32_e32 v89, v89, v93
	v_add_f32_e32 v90, v90, v94
	v_add_f32_e32 v91, v91, v95
	ds_bpermute_b32 v92, v9, v88
	ds_bpermute_b32 v93, v9, v89
	ds_bpermute_b32 v94, v9, v90
	ds_bpermute_b32 v95, v9, v91
	s_waitcnt lgkmcnt(0)
	v_add_f32_e32 v88, v88, v92
	v_add_f32_e32 v89, v89, v93
	v_add_f32_e32 v90, v90, v94
	v_add_f32_e32 v91, v91, v95
	ds_bpermute_b32 v92, v10, v88
	ds_bpermute_b32 v93, v10, v89
	ds_bpermute_b32 v94, v10, v90
	ds_bpermute_b32 v95, v10, v91
	s_waitcnt lgkmcnt(0)
	v_add_f32_e32 v88, v88, v92
	v_add_f32_e32 v89, v89, v93
	v_add_f32_e32 v90, v90, v94
	v_add_f32_e32 v91, v91, v95
	ds_bpermute_b32 v92, v11, v88
	ds_bpermute_b32 v93, v11, v89
	ds_bpermute_b32 v94, v11, v90
	ds_bpermute_b32 v95, v11, v91
	s_waitcnt lgkmcnt(0)
	v_add_f32_e32 v88, v88, v92
	v_add_f32_e32 v89, v89, v93
	v_add_f32_e32 v90, v90, v94
	v_add_f32_e32 v91, v91, v95
	ds_bpermute_b32 v92, v12, v88
	ds_bpermute_b32 v93, v12, v89
	ds_bpermute_b32 v94, v12, v90
	ds_bpermute_b32 v95, v12, v91
	s_waitcnt lgkmcnt(0)
	v_add_f32_e32 v88, v88, v92
	v_add_f32_e32 v89, v89, v93
	v_add_f32_e32 v90, v90, v94
	v_add_f32_e32 v91, v91, v95
	v_fmamk_f32 v88, v88, 0x3c800000, v15
	v_mul_f32_e32 v92, 0x4b800000, v88
	v_cmp_gt_f32_e32 vcc, s8, v88
	s_nop 1
	v_cndmask_b32_e32 v88, v88, v92, vcc
	v_rsq_f32_e32 v88, v88
	s_nop 0
	v_mul_f32_e32 v92, 0x45800000, v88
	v_cndmask_b32_e32 v88, v88, v92, vcc
	v_fmamk_f32 v89, v89, 0x3c800000, v15
	v_mul_f32_e32 v93, 0x4b800000, v89
	v_cmp_gt_f32_e32 vcc, s8, v89
	s_nop 1
	v_cndmask_b32_e32 v89, v89, v93, vcc
	v_rsq_f32_e32 v89, v89
	s_nop 0
	v_mul_f32_e32 v93, 0x45800000, v89
	v_cndmask_b32_e32 v89, v89, v93, vcc
	v_fmamk_f32 v90, v90, 0x3c800000, v15
	v_mul_f32_e32 v94, 0x4b800000, v90
	v_cmp_gt_f32_e32 vcc, s8, v90
	s_nop 1
	v_cndmask_b32_e32 v90, v90, v94, vcc
	v_rsq_f32_e32 v90, v90
	s_nop 0
	v_mul_f32_e32 v94, 0x45800000, v90
	v_cndmask_b32_e32 v90, v90, v94, vcc
	v_fmamk_f32 v91, v91, 0x3c800000, v15
	v_mul_f32_e32 v95, 0x4b800000, v91
	v_cmp_gt_f32_e32 vcc, s8, v91
	s_nop 1
	v_cndmask_b32_e32 v91, v91, v95, vcc
	v_rsq_f32_e32 v91, v91
	s_nop 0
	v_mul_f32_e32 v95, 0x45800000, v91
	v_cndmask_b32_e32 v91, v91, v95, vcc
	v_mul_f32_e32 v72, v88, v72
	v_mul_f32_e32 v73, v88, v73
	v_mul_f32_e32 v74, v88, v74
	v_mul_f32_e32 v75, v88, v75
	v_mul_f32_e32 v72, v32, v72
	v_mul_f32_e32 v73, v33, v73
	v_mul_f32_e32 v74, v34, v74
	v_mul_f32_e32 v75, v35, v75
	v_cvt_pk_bf16_f32 v96, v72, v73
	v_cvt_pk_bf16_f32 v97, v74, v75
	global_store_dwordx2 v[64:65], v[96:97], off
	v_mul_f32_e32 v76, v89, v76
	v_mul_f32_e32 v77, v89, v77
	v_mul_f32_e32 v78, v89, v78
	v_mul_f32_e32 v79, v89, v79
	v_mul_f32_e32 v76, v32, v76
	v_mul_f32_e32 v77, v33, v77
	v_mul_f32_e32 v78, v34, v78
	v_mul_f32_e32 v79, v35, v79
	v_cvt_pk_bf16_f32 v98, v76, v77
	v_cvt_pk_bf16_f32 v99, v78, v79
	global_store_dwordx2 v[66:67], v[98:99], off
	v_mul_f32_e32 v80, v90, v80
	v_mul_f32_e32 v81, v90, v81
	v_mul_f32_e32 v82, v90, v82
	v_mul_f32_e32 v83, v90, v83
	v_mul_f32_e32 v80, v32, v80
	v_mul_f32_e32 v81, v33, v81
	v_mul_f32_e32 v82, v34, v82
	v_mul_f32_e32 v83, v35, v83
	v_cvt_pk_bf16_f32 v100, v80, v81
	v_cvt_pk_bf16_f32 v101, v82, v83
	global_store_dwordx2 v[68:69], v[100:101], off
	v_mul_f32_e32 v84, v91, v84
	v_mul_f32_e32 v85, v91, v85
	v_mul_f32_e32 v86, v91, v86
	v_mul_f32_e32 v87, v91, v87
	v_mul_f32_e32 v84, v32, v84
	v_mul_f32_e32 v85, v33, v85
	v_mul_f32_e32 v86, v34, v86
	v_mul_f32_e32 v87, v35, v87
	v_cvt_pk_bf16_f32 v102, v84, v85
	v_cvt_pk_bf16_f32 v103, v86, v87
	global_store_dwordx2 v[70:71], v[102:103], off
	s_branch .Lkn4_loop
.Lkn4_rest:
	s_cmpk_gt_i32 s9, 0x7fff
	s_cbranch_scc1 .LBB0_140
